# attn a3 + nearp bias block without swap copies + non-fast tail rewrite (V prefetch, exp/PV interleave)
# speedup vs baseline: 1.0432x; 1.0046x over previous
.LBB0_1460:
	s_andn2_b64 vcc, exec, s[2:3]
	s_cbranch_vccnz .LBB0_1462
	v_lshl_add_u32 v252, v33, 2, s69
	v_add_u32_e32 v253, 0x80, v252
	ds_read2_b32 v[38:39], v253 offset0:32 offset1:31
	ds_read2_b32 v[36:37], v252 offset0:62 offset1:61
	ds_read2_b32 v[40:41], v252 offset0:56 offset1:55
	ds_read2_b32 v[34:35], v252 offset0:54 offset1:53
	ds_read2_b32 v[134:135], v252 offset0:48 offset1:47
	ds_read2_b32 v[44:45], v252 offset0:46 offset1:45
	ds_read2_b32 v[46:47], v252 offset0:40 offset1:39
	ds_read2_b32 v[42:43], v252 offset0:38 offset1:37
	s_waitcnt lgkmcnt(7)
	v_pk_fma_f32 v[38:39], v[0:1], s[44:45], v[38:39] op_sel_hi:[1,0,1]
	s_waitcnt lgkmcnt(6)
	v_pk_fma_f32 v[36:37], v[2:3], s[44:45], v[36:37] op_sel_hi:[1,0,1]
	v_max3_f32 v125, v38, s70, v39
	s_waitcnt lgkmcnt(5)
	v_pk_fma_f32 v[40:41], v[4:5], s[44:45], v[40:41] op_sel_hi:[1,0,1]
	v_max3_f32 v125, v125, v36, v37
	s_waitcnt lgkmcnt(4)
	v_pk_fma_f32 v[34:35], v[6:7], s[44:45], v[34:35] op_sel_hi:[1,0,1]
	v_max3_f32 v125, v125, v40, v41
	s_waitcnt lgkmcnt(3)
	v_pk_fma_f32 v[134:135], v[8:9], s[44:45], v[134:135] op_sel_hi:[1,0,1]
	v_max3_f32 v125, v125, v34, v35
	s_waitcnt lgkmcnt(2)
	v_pk_fma_f32 v[44:45], v[10:11], s[44:45], v[44:45] op_sel_hi:[1,0,1]
	v_max3_f32 v125, v125, v134, v135
	s_waitcnt lgkmcnt(1)
	v_pk_fma_f32 v[46:47], v[12:13], s[44:45], v[46:47] op_sel_hi:[1,0,1]
	v_max3_f32 v125, v125, v44, v45
	s_waitcnt lgkmcnt(0)
	v_pk_fma_f32 v[42:43], v[14:15], s[44:45], v[42:43] op_sel_hi:[1,0,1]
	v_max3_f32 v125, v125, v46, v47
	s_nop 0
	v_max3_f32 v125, v125, v42, v43
	ds_read2_b32 v[142:143], v252 offset0:32 offset1:31
	ds_read2_b32 v[138:139], v252 offset0:30 offset1:29
	ds_read2_b32 v[140:141], v252 offset0:24 offset1:23
	ds_read2_b32 v[136:137], v252 offset0:22 offset1:21
	ds_read2_b32 v[150:151], v252 offset0:16 offset1:15
	ds_read2_b32 v[146:147], v252 offset0:14 offset1:13
	ds_read2_b32 v[148:149], v252 offset0:8 offset1:7
	ds_read2_b32 v[144:145], v252 offset0:6 offset1:5
	s_waitcnt lgkmcnt(7)
	v_pk_fma_f32 v[142:143], v[16:17], s[44:45], v[142:143] op_sel_hi:[1,0,1]
	s_waitcnt lgkmcnt(6)
	v_pk_fma_f32 v[138:139], v[18:19], s[44:45], v[138:139] op_sel_hi:[1,0,1]
	v_max3_f32 v125, v125, v142, v143
	s_waitcnt lgkmcnt(5)
	v_pk_fma_f32 v[140:141], v[20:21], s[44:45], v[140:141] op_sel_hi:[1,0,1]
	v_max3_f32 v125, v125, v138, v139
	s_waitcnt lgkmcnt(4)
	v_pk_fma_f32 v[136:137], v[22:23], s[44:45], v[136:137] op_sel_hi:[1,0,1]
	v_max3_f32 v125, v125, v140, v141
	s_waitcnt lgkmcnt(3)
	v_pk_fma_f32 v[150:151], v[24:25], s[44:45], v[150:151] op_sel_hi:[1,0,1]
	v_max3_f32 v125, v125, v136, v137
	s_waitcnt lgkmcnt(2)
	v_pk_fma_f32 v[146:147], v[26:27], s[44:45], v[146:147] op_sel_hi:[1,0,1]
	v_max3_f32 v125, v125, v150, v151
	s_waitcnt lgkmcnt(1)
	v_pk_fma_f32 v[148:149], v[28:29], s[44:45], v[148:149] op_sel_hi:[1,0,1]
	v_max3_f32 v125, v125, v146, v147
	s_waitcnt lgkmcnt(0)
	v_pk_fma_f32 v[144:145], v[30:31], s[44:45], v[144:145] op_sel_hi:[1,0,1]
	v_max3_f32 v125, v125, v148, v149
	s_nop 0
	v_max3_f32 v129, v125, v144, v145

.LBB0_1465:
	v_lshrrev_b32_e32 v0, s40, v104
	v_and_b32_e32 v0, 1, v0
	v_cmp_eq_u32_e32 vcc, 1, v0
	s_or_b64 s[0:1], s[0:1], vcc
	v_cndmask_b32_e64 v0, v211, v129, s[0:1]
	ds_bpermute_b32 v1, v155, v0
	v_add_u32_e32 v252, s37, v204
	ds_read_b64_tr_b16 v[236:237], v252 offset:18432
	ds_read_b64_tr_b16 v[238:239], v252 offset:19584
	ds_read_b64_tr_b16 v[240:241], v252 offset:18496
	ds_read_b64_tr_b16 v[242:243], v252 offset:19648
	ds_read_b64_tr_b16 v[244:245], v252 offset:20736
	ds_read_b64_tr_b16 v[246:247], v252 offset:21888
	ds_read_b64_tr_b16 v[248:249], v252 offset:20800
	ds_read_b64_tr_b16 v[250:251], v252 offset:21952
	s_mov_b64 s[2:3], -1
	s_waitcnt lgkmcnt(8)
	v_max3_f32 v33, v123, v0, v1
	v_cmp_neq_f32_e32 vcc, s70, v33
	s_nop 1
	v_cndmask_b32_e32 v125, 0, v33, vcc
	v_cndmask_b32_e64 v253, v212, v125, s[0:1]
	v_sub_f32_e32 v0, v38, v253
	v_sub_f32_e32 v1, v39, v253
	v_sub_f32_e32 v2, v36, v253
	v_sub_f32_e32 v3, v37, v253
	v_sub_f32_e32 v4, v40, v253
	v_sub_f32_e32 v5, v41, v253
	v_sub_f32_e32 v6, v34, v253
	v_sub_f32_e32 v7, v35, v253
	v_sub_f32_e32 v8, v134, v253
	v_sub_f32_e32 v9, v135, v253
	v_sub_f32_e32 v10, v44, v253
	v_sub_f32_e32 v11, v45, v253
	v_sub_f32_e32 v12, v46, v253
	v_sub_f32_e32 v13, v47, v253
	v_sub_f32_e32 v14, v42, v253
	v_sub_f32_e32 v15, v43, v253
	v_sub_f32_e32 v16, v142, v253
	v_sub_f32_e32 v17, v143, v253
	v_sub_f32_e32 v18, v138, v253
	v_sub_f32_e32 v19, v139, v253
	v_sub_f32_e32 v20, v140, v253
	v_sub_f32_e32 v21, v141, v253
	v_sub_f32_e32 v22, v136, v253
	v_sub_f32_e32 v23, v137, v253
	v_sub_f32_e32 v24, v150, v253
	v_sub_f32_e32 v25, v151, v253
	v_sub_f32_e32 v26, v146, v253
	v_sub_f32_e32 v27, v147, v253
	v_sub_f32_e32 v28, v148, v253
	v_sub_f32_e32 v29, v149, v253
	v_sub_f32_e32 v30, v144, v253
	v_sub_f32_e32 v31, v145, v253
	v_sub_f32_e32 v34, v123, v125
	v_exp_f32_e32 v34, v34
	s_waitcnt lgkmcnt(6)
	ds_read_b64_tr_b16 v[134:135], v252 offset:23040
	ds_read_b64_tr_b16 v[136:137], v252 offset:24192
	ds_read_b64_tr_b16 v[138:139], v252 offset:23104
	ds_read_b64_tr_b16 v[140:141], v252 offset:24256
	ds_read_b64_tr_b16 v[142:143], v252 offset:25344
	ds_read_b64_tr_b16 v[144:145], v252 offset:26496
	ds_read_b64_tr_b16 v[146:147], v252 offset:25408
	ds_read_b64_tr_b16 v[148:149], v252 offset:26560
	v_cmp_neq_f32_e32 vcc, 1.0, v34
	v_mov_b32_e32 v37, 0
	s_cbranch_vccz .Lfa_norescale2
	v_pk_mul_f32 v[78:79], v[78:79], v[34:35] op_sel_hi:[1,0]
	v_pk_mul_f32 v[76:77], v[76:77], v[34:35] op_sel_hi:[1,0]
	v_pk_mul_f32 v[74:75], v[74:75], v[34:35] op_sel_hi:[1,0]
	v_pk_mul_f32 v[72:73], v[72:73], v[34:35] op_sel_hi:[1,0]
	v_pk_mul_f32 v[70:71], v[70:71], v[34:35] op_sel_hi:[1,0]
	v_pk_mul_f32 v[68:69], v[68:69], v[34:35] op_sel_hi:[1,0]
	v_pk_mul_f32 v[66:67], v[66:67], v[34:35] op_sel_hi:[1,0]
	v_pk_mul_f32 v[64:65], v[64:65], v[34:35] op_sel_hi:[1,0]
	v_pk_mul_f32 v[62:63], v[62:63], v[34:35] op_sel_hi:[1,0]
	v_pk_mul_f32 v[60:61], v[60:61], v[34:35] op_sel_hi:[1,0]
	v_pk_mul_f32 v[58:59], v[58:59], v[34:35] op_sel_hi:[1,0]
	v_pk_mul_f32 v[56:57], v[56:57], v[34:35] op_sel_hi:[1,0]
	v_pk_mul_f32 v[54:55], v[54:55], v[34:35] op_sel_hi:[1,0]
	v_pk_mul_f32 v[52:53], v[52:53], v[34:35] op_sel_hi:[1,0]
	v_pk_mul_f32 v[50:51], v[50:51], v[34:35] op_sel_hi:[1,0]
	v_pk_mul_f32 v[48:49], v[48:49], v[34:35] op_sel_hi:[1,0]
.Lfa_norescale2:
	v_exp_f32_e32 v0, v0
	v_exp_f32_e32 v1, v1
	v_add_f32_e32 v37, v0, v37
	v_exp_f32_e32 v2, v2
	v_add_f32_e32 v37, v1, v37
	v_exp_f32_e32 v3, v3
	v_add_f32_e32 v37, v2, v37
	v_exp_f32_e32 v4, v4
	v_add_f32_e32 v37, v3, v37
	v_exp_f32_e32 v5, v5
	v_add_f32_e32 v37, v4, v37
	v_exp_f32_e32 v6, v6
	v_add_f32_e32 v37, v5, v37
	v_exp_f32_e32 v7, v7
	v_add_f32_e32 v37, v6, v37
	s_nop 0
	v_add_f32_e32 v37, v7, v37
	v_cvt_pk_bf16_f32 v0, v0, v1
	v_cvt_pk_bf16_f32 v1, v2, v3
	v_cvt_pk_bf16_f32 v2, v4, v5
	v_cvt_pk_bf16_f32 v3, v6, v7
	s_waitcnt lgkmcnt(14)
	s_nop 0
	v_mfma_f32_32x32x16_bf16 v[64:79], v[236:239], v[0:3], v[64:79]
	s_waitcnt lgkmcnt(12)
	v_mfma_f32_32x32x16_bf16 v[48:63], v[240:243], v[0:3], v[48:63]
	v_exp_f32_e32 v8, v8
	v_exp_f32_e32 v9, v9
	v_add_f32_e32 v37, v8, v37
	v_exp_f32_e32 v10, v10
	v_add_f32_e32 v37, v9, v37
	v_exp_f32_e32 v11, v11
	v_add_f32_e32 v37, v10, v37
	v_exp_f32_e32 v12, v12
	v_add_f32_e32 v37, v11, v37
	v_exp_f32_e32 v13, v13
	v_add_f32_e32 v37, v12, v37
	v_exp_f32_e32 v14, v14
	v_add_f32_e32 v37, v13, v37
	v_exp_f32_e32 v15, v15
	v_add_f32_e32 v37, v14, v37
	s_nop 0
	v_add_f32_e32 v37, v15, v37
	v_cvt_pk_bf16_f32 v8, v8, v9
	v_cvt_pk_bf16_f32 v9, v10, v11
	v_cvt_pk_bf16_f32 v10, v12, v13
	v_cvt_pk_bf16_f32 v11, v14, v15
	s_waitcnt lgkmcnt(10)
	s_nop 0
	v_mfma_f32_32x32x16_bf16 v[64:79], v[244:247], v[8:11], v[64:79]
	s_waitcnt lgkmcnt(8)
	v_mfma_f32_32x32x16_bf16 v[48:63], v[248:251], v[8:11], v[48:63]
	v_exp_f32_e32 v16, v16
	v_exp_f32_e32 v17, v17
	v_add_f32_e32 v37, v16, v37
	v_exp_f32_e32 v18, v18
	v_add_f32_e32 v37, v17, v37
	v_exp_f32_e32 v19, v19
	v_add_f32_e32 v37, v18, v37
	v_exp_f32_e32 v20, v20
	v_add_f32_e32 v37, v19, v37
	v_exp_f32_e32 v21, v21
	v_add_f32_e32 v37, v20, v37
	v_exp_f32_e32 v22, v22
	v_add_f32_e32 v37, v21, v37
	v_exp_f32_e32 v23, v23
	v_add_f32_e32 v37, v22, v37
	s_nop 0
	v_add_f32_e32 v37, v23, v37
	v_cvt_pk_bf16_f32 v16, v16, v17
	v_cvt_pk_bf16_f32 v17, v18, v19
	v_cvt_pk_bf16_f32 v18, v20, v21
	v_cvt_pk_bf16_f32 v19, v22, v23
	s_waitcnt lgkmcnt(6)
	s_nop 0
	v_mfma_f32_32x32x16_bf16 v[64:79], v[134:137], v[16:19], v[64:79]
	s_waitcnt lgkmcnt(4)
	v_mfma_f32_32x32x16_bf16 v[48:63], v[138:141], v[16:19], v[48:63]
	v_exp_f32_e32 v24, v24
	v_exp_f32_e32 v25, v25
	v_add_f32_e32 v37, v24, v37
	v_exp_f32_e32 v26, v26
	v_add_f32_e32 v37, v25, v37
	v_exp_f32_e32 v27, v27
	v_add_f32_e32 v37, v26, v37
	v_exp_f32_e32 v28, v28
	v_add_f32_e32 v37, v27, v37
	v_exp_f32_e32 v29, v29
	v_add_f32_e32 v37, v28, v37
	v_exp_f32_e32 v30, v30
	v_add_f32_e32 v37, v29, v37
	v_exp_f32_e32 v31, v31
	v_add_f32_e32 v37, v30, v37
	s_nop 0
	v_add_f32_e32 v37, v31, v37
	v_cvt_pk_bf16_f32 v24, v24, v25
	v_cvt_pk_bf16_f32 v25, v26, v27
	v_cvt_pk_bf16_f32 v26, v28, v29
	v_cvt_pk_bf16_f32 v27, v30, v31
	s_waitcnt lgkmcnt(2)
	s_nop 0
	v_mfma_f32_32x32x16_bf16 v[64:79], v[142:145], v[24:27], v[64:79]
	s_waitcnt lgkmcnt(0)
	v_mfma_f32_32x32x16_bf16 v[48:63], v[146:149], v[24:27], v[48:63]
	v_fmac_f32_e32 v37, v121, v34
	v_mov_b32_e32 v123, v33
	v_mov_b32_e32 v121, v37
